# v29 + hg_cum column passes (hgA and hgC) with all eight LDS row-pair reads in flight and counted waits; slab-0 saveB copy as one round trip instead of a per-lane load-wait-store loop
# baseline (speedup 1.0000x reference)
; __device__ __forceinline__ void prep_item(const Bufs& B, int l, int s, int it, unsigned char* shm, const bf16x8 (&w2f)[4][2], const bf16x8 (&a2f)[4][2], const PrepRegs& R) {
;     ...
;     if (s == 0 && tl0 + 16 == 2048) for (int c = tid; c < 1792; c += 512) B.saveB[b * 1792 + c] = B.bufB[(size_t)(b * 2048 + 2047) * 1792 + c];
.LBB0_524:
	s_or_b64 exec, exec, s[2:3]
	s_cmpk_eq_i32 s90, 0x7f0
	s_cselect_b64 s[2:3], -1, 0
	s_movk_i32 s38, 0x700
	s_and_b64 s[2:3], s[64:65], s[2:3]
	v_cmp_gt_i32_e32 vcc, s38, v136
	s_and_b64 s[38:39], s[2:3], vcc
	s_and_saveexec_b64 s[2:3], s[38:39]
	s_cbranch_execz .LBB0_471
	s_lshl_b32 s38, s89, 11
	v_ashrrev_i32_e32 v137, 31, v136
	s_add_u32 s16, s27, s16
	v_lshlrev_b64 v[74:75], 1, v[136:137]
	s_addc_u32 s17, s29, s17
	s_mul_i32 s89, s89, 0x700000
	v_lshl_add_u64 v[72:73], s[16:17], 0, v[74:75]
	s_mul_hi_i32 s17, s38, 0xe00
	s_add_u32 s16, s87, s89
	s_addc_u32 s17, s88, s17
	v_add_u32_e32 v76, 0xfffffe00, v136
	v_lshl_add_u64 v[74:75], s[16:17], 0, v[74:75]
	s_mov_b64 s[16:17], 0
	global_load_ushort v77, v[74:75], off
	global_load_ushort v78, v[74:75], off offset:1024
	global_load_ushort v79, v[74:75], off offset:2048
	v_cmp_gt_i32_e32 vcc, 0x100, v136
	s_and_saveexec_b64 s[16:17], vcc
	global_load_ushort v80, v[74:75], off offset:3072
	s_waitcnt vmcnt(0)
	global_store_short v[72:73], v80, off offset:3072
	s_mov_b64 exec, s[16:17]
	global_store_short v[72:73], v77, off
	global_store_short v[72:73], v78, off offset:1024
	global_store_short v[72:73], v79, off offset:2048
	s_branch .LBB0_471

; __device__ __forceinline__ void unpack8(const u32x4& w, f32x4& v0, f32x4& v1) { v0[0] = bflo(w.x); v0[1] = bfhi(w.x); v0[2] = bflo(w.y); v0[3] = bfhi(w.y); v1[0] = bflo(w.z); v1[1] = bfhi(w.z); v1[2] = bflo(w.w); v1[3] = bfhi(w.w); }
; __device__ __forceinline__ void hg_cum(const u32x4 (&ev)[2], int l, int h, const float* hlb, float* cumS, float* lbS, int tid) {
;     ...
; #pragma unroll
;     for (int q = 0; q < 2; ++q) {
;         const int idx = tid + 512 * q, t = idx >> 4, k8 = (idx & 15) * 8;
;         f32x4 a, bb; unpack8(ev[q], a, bb);
;         const f32x4 l0 = *(const f32x4*)(lbS + k8), l1 = *(const f32x4*)(lbS + k8 + 4);
; #pragma unroll
;         for (int j = 0; j < 4; ++j) { a[j] = __logf(fmaxf(1.0f - l0[j] * a[j], 1e-30f)); bb[j] = __logf(fmaxf(1.0f - l1[j] * bb[j], 1e-30f)); }
;         *(f32x4*)(cumS + t * 128 + k8) = a; *(f32x4*)(cumS + t * 128 + k8 + 4) = bb;
.LBB0_535:
	s_or_b64 exec, exec, s[2:3]
	v_lshlrev_b32_e32 v51, 3, v42
	v_and_b32_e32 v43, 0x78, v51
	v_lshl_add_u32 v50, v43, 2, 0
	v_add_u32_e32 v38, 0x11000, v50
	s_waitcnt lgkmcnt(0)
	s_barrier
	s_waitcnt vmcnt(4)
	v_lshlrev_b32_e32 v47, 16, v30
	v_and_b32_e32 v60, 0xffff0000, v30
	v_lshlrev_b32_e32 v54, 16, v31
	v_and_b32_e32 v52, 0xffff0000, v31
	ds_read_b128 v[34:37], v38
	ds_read_b128 v[30:33], v38 offset:16
	v_lshlrev_b32_e32 v39, 16, v28
	v_and_b32_e32 v46, 0xffff0000, v28
	v_lshlrev_b32_e32 v56, 16, v29
	s_waitcnt lgkmcnt(1)
	v_fma_f32 v28, -v34, v39, 1.0
	v_max_f32_e32 v28, 0xda24260, v28
	v_cmp_gt_f32_e32 vcc, s33, v28
	v_and_b32_e32 v53, 0xffff0000, v29
	v_lshlrev_b32_e32 v64, 16, v24
	v_cndmask_b32_e64 v29, 0, 32, vcc
	v_ldexp_f32 v28, v28, v29
	v_log_f32_e32 v28, v28
	v_and_b32_e32 v62, 0xffff0000, v24
	v_lshlrev_b32_e32 v59, 16, v25
	v_and_b32_e32 v57, 0xffff0000, v25
	v_mul_f32_e32 v29, 0x3f317217, v28
	v_fma_f32 v29, v28, s79, -v29
	v_fmac_f32_e32 v29, 0x3377d1cf, v28
	v_fmac_f32_e32 v29, 0x3f317217, v28
	v_cmp_lt_f32_e64 s[40:41], |v28|, s80
	v_lshlrev_b32_e32 v63, 16, v26
	v_and_b32_e32 v61, 0xffff0000, v26
	v_cndmask_b32_e64 v28, v28, v29, s[40:41]
	v_cndmask_b32_e32 v29, 0, v212, vcc
	v_sub_f32_e32 v28, v28, v29
	s_waitcnt lgkmcnt(0)
	v_fma_f32 v29, -v30, v47, 1.0
	v_max_f32_e32 v29, 0xda24260, v29
	v_cmp_gt_f32_e32 vcc, s33, v29
	v_lshlrev_b32_e32 v58, 16, v27
	v_and_b32_e32 v55, 0xffff0000, v27
	v_cndmask_b32_e64 v30, 0, 32, vcc
	v_ldexp_f32 v29, v29, v30
	v_log_f32_e32 v29, v29
	s_nop 0
	v_mul_f32_e32 v30, 0x3f317217, v29
	v_fma_f32 v30, v29, s79, -v30
	v_fmac_f32_e32 v30, 0x3377d1cf, v29
	v_fmac_f32_e32 v30, 0x3f317217, v29
	v_cmp_lt_f32_e64 s[40:41], |v29|, s80
	s_nop 1
	v_cndmask_b32_e64 v29, v29, v30, s[40:41]
	v_cndmask_b32_e32 v30, 0, v212, vcc
	v_sub_f32_e32 v34, v29, v30
	v_fma_f32 v29, -v35, v46, 1.0
	v_max_f32_e32 v29, 0xda24260, v29
	v_cmp_gt_f32_e32 vcc, s33, v29
	s_nop 1
	v_cndmask_b32_e64 v30, 0, 32, vcc
	v_ldexp_f32 v29, v29, v30
	v_log_f32_e32 v29, v29
	s_nop 0
	v_mul_f32_e32 v30, 0x3f317217, v29
	v_fma_f32 v30, v29, s79, -v30
	v_fmac_f32_e32 v30, 0x3377d1cf, v29
	v_fmac_f32_e32 v30, 0x3f317217, v29
	v_cmp_lt_f32_e64 s[40:41], |v29|, s80
	s_nop 1
	v_cndmask_b32_e64 v29, v29, v30, s[40:41]
	v_cndmask_b32_e32 v30, 0, v212, vcc
	v_sub_f32_e32 v29, v29, v30
	v_fma_f32 v30, -v31, v60, 1.0
	v_max_f32_e32 v30, 0xda24260, v30
	v_cmp_gt_f32_e32 vcc, s33, v30
	s_nop 1
	v_cndmask_b32_e64 v31, 0, 32, vcc
	v_ldexp_f32 v30, v30, v31
	v_log_f32_e32 v30, v30
	s_nop 0
	v_mul_f32_e32 v31, 0x3f317217, v30
	v_fma_f32 v31, v30, s79, -v31
	v_fmac_f32_e32 v31, 0x3377d1cf, v30
	v_fmac_f32_e32 v31, 0x3f317217, v30
	v_cmp_lt_f32_e64 s[40:41], |v30|, s80
	s_nop 1
	v_cndmask_b32_e64 v30, v30, v31, s[40:41]
	v_cndmask_b32_e32 v31, 0, v212, vcc
	v_sub_f32_e32 v35, v30, v31
	v_fma_f32 v30, -v36, v56, 1.0
	v_max_f32_e32 v30, 0xda24260, v30
	v_cmp_gt_f32_e32 vcc, s33, v30
	s_nop 1
	v_cndmask_b32_e64 v31, 0, 32, vcc
	v_ldexp_f32 v30, v30, v31
	v_log_f32_e32 v30, v30
	s_nop 0
	v_mul_f32_e32 v31, 0x3f317217, v30
	v_fma_f32 v31, v30, s79, -v31
	v_fmac_f32_e32 v31, 0x3377d1cf, v30
	v_fmac_f32_e32 v31, 0x3f317217, v30
	v_cmp_lt_f32_e64 s[40:41], |v30|, s80
	s_nop 1
	v_cndmask_b32_e64 v30, v30, v31, s[40:41]
	v_cndmask_b32_e32 v31, 0, v212, vcc
	v_sub_f32_e32 v30, v30, v31
	v_fma_f32 v31, -v32, v54, 1.0
	v_max_f32_e32 v31, 0xda24260, v31
	v_cmp_gt_f32_e32 vcc, s33, v31
	s_nop 1
	v_cndmask_b32_e64 v32, 0, 32, vcc
	v_ldexp_f32 v31, v31, v32
	v_log_f32_e32 v31, v31
	s_nop 0
	v_mul_f32_e32 v32, 0x3f317217, v31
	v_fma_f32 v32, v31, s79, -v32
	v_fmac_f32_e32 v32, 0x3377d1cf, v31
	v_fmac_f32_e32 v32, 0x3f317217, v31
	v_cmp_lt_f32_e64 s[40:41], |v31|, s80
	s_nop 1
	v_cndmask_b32_e64 v31, v31, v32, s[40:41]
	v_cndmask_b32_e32 v32, 0, v212, vcc
	v_sub_f32_e32 v36, v31, v32
	v_fma_f32 v31, -v37, v53, 1.0
	v_max_f32_e32 v31, 0xda24260, v31
	v_cmp_gt_f32_e32 vcc, s33, v31
	s_nop 1
	v_cndmask_b32_e64 v32, 0, 32, vcc
	v_ldexp_f32 v31, v31, v32
	v_log_f32_e32 v31, v31
	s_nop 0
	v_mul_f32_e32 v32, 0x3f317217, v31
	v_fma_f32 v32, v31, s79, -v32
	v_fmac_f32_e32 v32, 0x3377d1cf, v31
	v_fmac_f32_e32 v32, 0x3f317217, v31
	v_cmp_lt_f32_e64 s[40:41], |v31|, s80
	s_nop 1
	v_cndmask_b32_e64 v31, v31, v32, s[40:41]
	v_cndmask_b32_e32 v32, 0, v212, vcc
	v_sub_f32_e32 v31, v31, v32
	v_fma_f32 v32, -v33, v52, 1.0
	v_max_f32_e32 v32, 0xda24260, v32
	v_cmp_gt_f32_e32 vcc, s33, v32
	s_nop 1
	v_cndmask_b32_e64 v33, 0, 32, vcc
	v_ldexp_f32 v32, v32, v33
	v_log_f32_e32 v32, v32
	s_nop 0
	v_mul_f32_e32 v33, 0x3f317217, v32
	v_fma_f32 v33, v32, s79, -v33
	v_fmac_f32_e32 v33, 0x3377d1cf, v32
	v_fmac_f32_e32 v33, 0x3f317217, v32
	v_cmp_lt_f32_e64 s[40:41], |v32|, s80
	s_nop 1
	v_cndmask_b32_e64 v32, v32, v33, s[40:41]
	v_cndmask_b32_e32 v33, 0, v212, vcc
	v_sub_f32_e32 v37, v32, v33
	v_lshlrev_b32_e32 v32, 5, v42
	v_and_b32_e32 v32, 0xfffffe00, v32
	v_add_u32_e32 v32, v50, v32
	ds_write_b128 v32, v[28:31]
	ds_write_b128 v32, v[34:37] offset:16
	ds_read_b128 v[28:31], v38
	ds_read_b128 v[24:27], v38 offset:16
	s_waitcnt lgkmcnt(1)
	v_fma_f32 v28, -v28, v64, 1.0
	v_max_f32_e32 v28, 0xda24260, v28
	v_cmp_gt_f32_e32 vcc, s33, v28
	s_waitcnt lgkmcnt(0)
; __device__ __forceinline__ void unpack8(const u32x4& w, f32x4& v0, f32x4& v1) { v0[0] = bflo(w.x); v0[1] = bfhi(w.x); v0[2] = bflo(w.y); v0[3] = bfhi(w.y); v1[0] = bflo(w.z); v1[1] = bfhi(w.z); v1[2] = bflo(w.w); v1[3] = bfhi(w.w); }
; __device__ __forceinline__ void hg_cum(const u32x4 (&ev)[2], int l, int h, const float* hlb, float* cumS, float* lbS, int tid) {
;     ...
; #pragma unroll
;     for (int q = 0; q < 2; ++q) {
;         const int idx = tid + 512 * q, t = idx >> 4, k8 = (idx & 15) * 8;
;         f32x4 a, bb; unpack8(ev[q], a, bb);
;         const f32x4 l0 = *(const f32x4*)(lbS + k8), l1 = *(const f32x4*)(lbS + k8 + 4);
; #pragma unroll
;         for (int j = 0; j < 4; ++j) { a[j] = __logf(fmaxf(1.0f - l0[j] * a[j], 1e-30f)); bb[j] = __logf(fmaxf(1.0f - l1[j] * bb[j], 1e-30f)); }
;         *(f32x4*)(cumS + t * 128 + k8) = a; *(f32x4*)(cumS + t * 128 + k8 + 4) = bb;
;     }
;     __syncthreads();
;     const int k = tid & 127, seg = tid >> 7;
;     { float run = 0.f;
; #pragma unroll
;       for (int tt = 0; tt < 16; ++tt) { const int t = seg * 16 + tt; run += cumS[t * 128 + k]; cumS[t * 128 + k] = run; } }
	v_fma_f32 v24, -v24, v63, 1.0
	v_max_f32_e32 v24, 0xda24260, v24
	v_cndmask_b32_e64 v33, 0, 32, vcc
	v_ldexp_f32 v28, v28, v33
	v_log_f32_e32 v28, v28
	v_fma_f32 v29, -v29, v62, 1.0
	v_max_f32_e32 v29, 0xda24260, v29
	v_fma_f32 v25, -v25, v61, 1.0
	v_mul_f32_e32 v33, 0x3f317217, v28
	v_fma_f32 v33, v28, s79, -v33
	v_fmac_f32_e32 v33, 0x3377d1cf, v28
	v_fmac_f32_e32 v33, 0x3f317217, v28
	v_cmp_lt_f32_e64 s[40:41], |v28|, s80
	v_max_f32_e32 v25, 0xda24260, v25
	v_fma_f32 v30, -v30, v59, 1.0
	v_cndmask_b32_e64 v28, v28, v33, s[40:41]
	v_cndmask_b32_e32 v33, 0, v212, vcc
	v_cmp_gt_f32_e32 vcc, s33, v24
	v_sub_f32_e32 v28, v28, v33
	v_max_f32_e32 v30, 0xda24260, v30
	v_cndmask_b32_e64 v33, 0, 32, vcc
	v_ldexp_f32 v24, v24, v33
	v_log_f32_e32 v24, v24
	v_fma_f32 v26, -v26, v58, 1.0
	v_max_f32_e32 v26, 0xda24260, v26
	v_fma_f32 v31, -v31, v57, 1.0
	v_mul_f32_e32 v33, 0x3f317217, v24
	v_fma_f32 v33, v24, s79, -v33
	v_fmac_f32_e32 v33, 0x3377d1cf, v24
	v_fmac_f32_e32 v33, 0x3f317217, v24
	v_cmp_lt_f32_e64 s[40:41], |v24|, s80
	v_max_f32_e32 v31, 0xda24260, v31
	v_fma_f32 v27, -v27, v55, 1.0
	v_cndmask_b32_e64 v24, v24, v33, s[40:41]
	v_cndmask_b32_e32 v33, 0, v212, vcc
	v_cmp_gt_f32_e32 vcc, s33, v29
	v_sub_f32_e32 v24, v24, v33
	v_max_f32_e32 v27, 0xda24260, v27
	v_cndmask_b32_e64 v33, 0, 32, vcc
	v_ldexp_f32 v29, v29, v33
	v_log_f32_e32 v29, v29
	s_nop 0
	v_mul_f32_e32 v33, 0x3f317217, v29
	v_fma_f32 v33, v29, s79, -v33
	v_fmac_f32_e32 v33, 0x3377d1cf, v29
	v_fmac_f32_e32 v33, 0x3f317217, v29
	v_cmp_lt_f32_e64 s[40:41], |v29|, s80
	s_nop 1
	v_cndmask_b32_e64 v29, v29, v33, s[40:41]
	v_cndmask_b32_e32 v33, 0, v212, vcc
	v_cmp_gt_f32_e32 vcc, s33, v25
	v_sub_f32_e32 v29, v29, v33
	s_nop 0
	v_cndmask_b32_e64 v33, 0, 32, vcc
	v_ldexp_f32 v25, v25, v33
	v_log_f32_e32 v25, v25
	s_nop 0
	v_mul_f32_e32 v33, 0x3f317217, v25
	v_fma_f32 v33, v25, s79, -v33
	v_fmac_f32_e32 v33, 0x3377d1cf, v25
	v_fmac_f32_e32 v33, 0x3f317217, v25
	v_cmp_lt_f32_e64 s[40:41], |v25|, s80
	s_nop 1
	v_cndmask_b32_e64 v25, v25, v33, s[40:41]
	v_cndmask_b32_e32 v33, 0, v212, vcc
	v_cmp_gt_f32_e32 vcc, s33, v30
	v_sub_f32_e32 v25, v25, v33
	s_nop 0
	v_cndmask_b32_e64 v33, 0, 32, vcc
	v_ldexp_f32 v30, v30, v33
	v_log_f32_e32 v30, v30
	s_nop 0
	v_mul_f32_e32 v33, 0x3f317217, v30
	v_fma_f32 v33, v30, s79, -v33
	v_fmac_f32_e32 v33, 0x3377d1cf, v30
	v_fmac_f32_e32 v33, 0x3f317217, v30
	v_cmp_lt_f32_e64 s[40:41], |v30|, s80
	s_nop 1
	v_cndmask_b32_e64 v30, v30, v33, s[40:41]
	v_cndmask_b32_e32 v33, 0, v212, vcc
	v_cmp_gt_f32_e32 vcc, s33, v26
	v_sub_f32_e32 v30, v30, v33
	s_nop 0
	v_cndmask_b32_e64 v33, 0, 32, vcc
	v_ldexp_f32 v26, v26, v33
	v_log_f32_e32 v26, v26
	s_nop 0
	v_mul_f32_e32 v33, 0x3f317217, v26
	v_fma_f32 v33, v26, s79, -v33
	v_fmac_f32_e32 v33, 0x3377d1cf, v26
	v_fmac_f32_e32 v33, 0x3f317217, v26
	v_cmp_lt_f32_e64 s[40:41], |v26|, s80
	s_nop 1
	v_cndmask_b32_e64 v26, v26, v33, s[40:41]
	v_cndmask_b32_e32 v33, 0, v212, vcc
	v_cmp_gt_f32_e32 vcc, s33, v31
	v_sub_f32_e32 v26, v26, v33
	s_nop 0
	v_cndmask_b32_e64 v33, 0, 32, vcc
	v_ldexp_f32 v31, v31, v33
	v_log_f32_e32 v31, v31
	s_nop 0
	v_mul_f32_e32 v33, 0x3f317217, v31
	v_fma_f32 v33, v31, s79, -v33
	v_fmac_f32_e32 v33, 0x3377d1cf, v31
	v_fmac_f32_e32 v33, 0x3f317217, v31
	v_cmp_lt_f32_e64 s[40:41], |v31|, s80
	s_nop 1
	v_cndmask_b32_e64 v31, v31, v33, s[40:41]
	v_cndmask_b32_e32 v33, 0, v212, vcc
	v_cmp_gt_f32_e32 vcc, s33, v27
	v_sub_f32_e32 v31, v31, v33
	s_nop 0
	v_cndmask_b32_e64 v33, 0, 32, vcc
	v_ldexp_f32 v27, v27, v33
	v_log_f32_e32 v27, v27
	s_nop 0
	v_mul_f32_e32 v33, 0x3f317217, v27
	v_fma_f32 v33, v27, s79, -v33
	v_fmac_f32_e32 v33, 0x3377d1cf, v27
	v_fmac_f32_e32 v33, 0x3f317217, v27
	v_cmp_lt_f32_e64 s[40:41], |v27|, s80
	s_nop 1
	v_cndmask_b32_e64 v27, v27, v33, s[40:41]
	v_cndmask_b32_e32 v33, 0, v212, vcc
	v_sub_f32_e32 v27, v27, v33
	ds_write_b128 v32, v[28:31] offset:16384
	ds_write_b128 v32, v[24:27] offset:16400
	v_and_b32_e32 v27, 0x7f, v42
	v_ashrrev_i32_e32 v26, 7, v42
	v_lshlrev_b32_e32 v24, 13, v26
	v_lshlrev_b32_e32 v25, 2, v27
	v_add3_u32 v24, 0, v24, v25
	s_waitcnt lgkmcnt(0)
	s_barrier
	ds_read2st64_b32 v[104:105], v24 offset1:2
	ds_read2st64_b32 v[106:107], v24 offset0:4 offset1:6
	ds_read2st64_b32 v[108:109], v24 offset0:8 offset1:10
	ds_read2st64_b32 v[110:111], v24 offset0:12 offset1:14
	ds_read2st64_b32 v[112:113], v24 offset0:16 offset1:18
	ds_read2st64_b32 v[114:115], v24 offset0:20 offset1:22
	ds_read2st64_b32 v[116:117], v24 offset0:24 offset1:26
	ds_read2st64_b32 v[118:119], v24 offset0:28 offset1:30
	v_cmp_lt_i32_e32 vcc, 0, v26
	s_waitcnt lgkmcnt(7)
	v_add_f32_e32 v104, 0, v104
	v_add_f32_e32 v105, v104, v105
	ds_write2st64_b32 v24, v104, v105 offset1:2
	s_waitcnt lgkmcnt(7)
	v_add_f32_e32 v106, v105, v106
	v_add_f32_e32 v107, v106, v107
	ds_write2st64_b32 v24, v106, v107 offset0:4 offset1:6
	s_waitcnt lgkmcnt(7)
	v_add_f32_e32 v108, v107, v108
	v_add_f32_e32 v109, v108, v109
	ds_write2st64_b32 v24, v108, v109 offset0:8 offset1:10
	s_waitcnt lgkmcnt(7)
	v_add_f32_e32 v110, v109, v110
	v_add_f32_e32 v111, v110, v111
	ds_write2st64_b32 v24, v110, v111 offset0:12 offset1:14
	s_waitcnt lgkmcnt(7)
	v_add_f32_e32 v112, v111, v112
	v_add_f32_e32 v113, v112, v113
	ds_write2st64_b32 v24, v112, v113 offset0:16 offset1:18
	s_waitcnt lgkmcnt(7)
	v_add_f32_e32 v114, v113, v114
	v_add_f32_e32 v115, v114, v115
	ds_write2st64_b32 v24, v114, v115 offset0:20 offset1:22
	s_waitcnt lgkmcnt(7)
	v_add_f32_e32 v116, v115, v116
	v_add_f32_e32 v117, v116, v117
	ds_write2st64_b32 v24, v116, v117 offset0:24 offset1:26
	s_waitcnt lgkmcnt(7)
	v_add_f32_e32 v25, v117, v118
	v_add_f32_e32 v28, v25, v119
	ds_write2st64_b32 v24, v25, v28 offset0:28 offset1:30
	v_mov_b32_e32 v25, 0
	s_waitcnt lgkmcnt(0)
	s_barrier
	s_and_saveexec_b64 s[2:3], vcc
	s_cbranch_execz .LBB0_539
	v_lshl_add_u32 v27, v27, 2, s60
	v_mov_b32_e32 v25, 0
	s_mov_b64 s[34:35], 0

; __device__ __forceinline__ void hg_cum(const u32x4 (&ev)[2], int l, int h, const float* hlb, float* cumS, float* lbS, int tid) {
;     ...
;     float off = 0.f;
;     for (int sp = 0; sp < seg; ++sp) off += cumS[(16 * sp + 15) * 128 + k];
;     __syncthreads();
; #pragma unroll
;     for (int tt = 0; tt < 16; ++tt) cumS[(seg * 16 + tt) * 128 + k] += off;
;     __syncthreads();
.LBB0_539:
	s_or_b64 exec, exec, s[2:3]
	s_barrier
	ds_read2st64_b32 v[104:105], v24 offset1:2
	ds_read2st64_b32 v[106:107], v24 offset0:4 offset1:6
	ds_read2st64_b32 v[108:109], v24 offset0:8 offset1:10
	ds_read2st64_b32 v[110:111], v24 offset0:12 offset1:14
	ds_read2st64_b32 v[112:113], v24 offset0:16 offset1:18
	ds_read2st64_b32 v[114:115], v24 offset0:20 offset1:22
	ds_read2st64_b32 v[116:117], v24 offset0:24 offset1:26
	ds_read2st64_b32 v[118:119], v24 offset0:28 offset1:30
	s_movk_i32 s2, 0x8c
	v_mad_u32_u24 v65, v43, s2, v50
	s_movk_i32 s2, 0xff74
	v_mad_i32_i24 v69, v43, s2, v65
	v_mad_u32_u24 v70, v43, s76, s76
	s_waitcnt lgkmcnt(7)
	v_add_f32_e32 v104, v25, v104
	v_add_f32_e32 v105, v25, v105
	ds_write2st64_b32 v24, v104, v105 offset1:2
	s_waitcnt lgkmcnt(7)
	v_add_f32_e32 v106, v25, v106
	v_add_f32_e32 v107, v25, v107
	ds_write2st64_b32 v24, v106, v107 offset0:4 offset1:6
	s_waitcnt lgkmcnt(7)
	v_add_f32_e32 v108, v25, v108
	v_add_f32_e32 v109, v25, v109
	ds_write2st64_b32 v24, v108, v109 offset0:8 offset1:10
	s_waitcnt lgkmcnt(7)
	v_add_f32_e32 v110, v25, v110
	v_add_f32_e32 v111, v25, v111
	ds_write2st64_b32 v24, v110, v111 offset0:12 offset1:14
	s_waitcnt lgkmcnt(7)
	v_add_f32_e32 v112, v25, v112
	v_add_f32_e32 v113, v25, v113
	ds_write2st64_b32 v24, v112, v113 offset0:16 offset1:18
	s_waitcnt lgkmcnt(7)
	v_add_f32_e32 v114, v25, v114
	v_add_f32_e32 v115, v25, v115
	ds_write2st64_b32 v24, v114, v115 offset0:20 offset1:22
	s_waitcnt lgkmcnt(7)
	v_add_f32_e32 v116, v25, v116
	v_add_f32_e32 v117, v25, v117
	ds_write2st64_b32 v24, v116, v117 offset0:24 offset1:26
	s_waitcnt lgkmcnt(7)
	v_add_f32_e32 v26, v25, v118
	v_add_f32_e32 v25, v25, v119
	ds_write2st64_b32 v24, v26, v25 offset0:28 offset1:30
	v_ashrrev_i32_e32 v24, 4, v42
	v_bitop3_b32 v25, v51, v24, 56 bitop3:0x6c
	s_waitcnt lgkmcnt(0)
	s_barrier
; __device__ __forceinline__ bf16_t f2bf(float f) { unsigned u = __float_as_uint(f); u += 0x7FFFu + ((u >> 16) & 1u); return (bf16_t)(u >> 16); }
; __device__ __forceinline__ void unpack8(const u32x4& w, f32x4& v0, f32x4& v1) { v0[0] = bflo(w.x); v0[1] = bfhi(w.x); v0[2] = bflo(w.y); v0[3] = bfhi(w.y); v1[0] = bflo(w.z); v1[1] = bfhi(w.z); v1[2] = bflo(w.w); v1[3] = bfhi(w.w); }
; __device__ __forceinline__ void hgA_item(const Bufs& B, int l, int it, unsigned char* shm, const float* hlb, const HgRegs& R) {
;     ...
; #pragma unroll
;     for (int q = 0; q < 2; ++q) {
;         const int idx = tid + 512 * q, t = idx >> 4, k8 = (idx & 15) * 8;
;         f32x4 a, bb; unpack8(R.ev[q], a, bb);
;         const u32x4 iw = R.iv[q];
;         const int tx = t ^ (((k8 >> 3) & 7) << 3);
; #pragma unroll
;         for (int j = 0; j < 4; ++j) {
;             kdT[(k8 + j) * 72 + tx] = f2bf(lbS[k8 + j] * a[j] * __expf(cumS[63 * 128 + k8 + j] - cumS[t * 128 + k8 + j]));
;             kdT[(k8 + 4 + j) * 72 + tx] = f2bf(lbS[k8 + 4 + j] * bb[j] * __expf(cumS[63 * 128 + k8 + 4 + j] - cumS[t * 128 + k8 + 4 + j]));
;         }
;         iT[(k8 + 0) * 72 + tx] = (bf16_t)(iw.x & 0xffffu); iT[(k8 + 1) * 72 + tx] = (bf16_t)(iw.x >> 16); iT[(k8 + 2) * 72 + tx] = (bf16_t)(iw.y & 0xffffu); iT[(k8 + 3) * 72 + tx] = (bf16_t)(iw.y >> 16);
;         iT[(k8 + 4) * 72 + tx] = (bf16_t)(iw.z & 0xffffu); iT[(k8 + 5) * 72 + tx] = (bf16_t)(iw.z >> 16); iT[(k8 + 6) * 72 + tx] = (bf16_t)(iw.w & 0xffffu); iT[(k8 + 7) * 72 + tx] = (bf16_t)(iw.w >> 16);
;     }
;     if (tid < 128) B.DEC[it * 128 + tid] = __expf(cumS[63 * 128 + tid]);
	v_lshl_add_u32 v28, v24, 9, v50
	v_lshlrev_b32_e32 v66, 1, v25
	ds_read_b128 v[24:27], v38
	v_add_u32_e32 v67, 0, v66
	s_waitcnt lgkmcnt(0)
	v_mul_f32_e32 v29, v24, v39
	ds_read_b128 v[36:39], v28
	ds_read_b128 v[32:35], v28 offset:16
	v_add_u32_e32 v28, 0x7c00, v50
	ds_read2_b32 v[44:45], v28 offset0:128 offset1:132
	v_mul_f32_e32 v53, v27, v53
	v_mul_f32_e32 v24, v24, v64
	s_waitcnt lgkmcnt(0)
	v_sub_f32_e32 v28, v44, v36
	v_mul_f32_e32 v28, 0x3fb8aa3b, v28
	v_exp_f32_e32 v28, v28
	v_sub_f32_e32 v32, v45, v32
	v_mul_f32_e32 v32, 0x3fb8aa3b, v32
	v_exp_f32_e32 v32, v32
	v_mul_f32_e32 v28, v29, v28
	v_bfe_u32 v29, v28, 16, 1
	v_add3_u32 v28, v28, v29, s78
	v_mad_u32_u24 v29, v43, s76, v67
	ds_write_b16_d16_hi v29, v28 offset:32768
	v_add_u32_e32 v28, 0x11010, v50
	ds_read_b128 v[28:31], v28
	s_waitcnt lgkmcnt(0)
	v_mul_f32_e32 v36, v28, v47
	v_mul_f32_e32 v32, v36, v32
	v_bfe_u32 v36, v32, 16, 1
	v_add3_u32 v32, v32, v36, s78
	v_mov_b32_e32 v36, 0x240
	v_mad_u32_u24 v68, v43, s76, v36
	v_add_u32_e32 v36, v67, v68
	ds_write_b16_d16_hi v36, v32 offset:32768
	v_add_u32_e32 v36, 0x7e04, v69
	v_mul_f32_e32 v32, v25, v46
	ds_read2_b32 v[46:47], v36 offset1:1
	s_waitcnt lgkmcnt(0)
	v_sub_f32_e32 v36, v46, v37
	v_mul_f32_e32 v36, 0x3fb8aa3b, v36
	v_exp_f32_e32 v36, v36
	s_nop 0
	v_mul_f32_e32 v32, v32, v36
	v_bfe_u32 v36, v32, 16, 1
	v_add3_u32 v32, v32, v36, s78
	v_add_u32_e32 v36, v67, v70
	ds_write_b16_d16_hi v36, v32 offset:32768
	v_add_u32_e32 v36, 0x7e14, v69
	ds_read2_b32 v[36:37], v36 offset1:1
	v_mul_f32_e32 v32, v29, v60
	s_waitcnt lgkmcnt(0)
	v_sub_f32_e32 v33, v36, v33
	v_mul_f32_e32 v33, 0x3fb8aa3b, v33
	v_exp_f32_e32 v33, v33
	s_nop 0
	v_mul_f32_e32 v32, v32, v33
	v_bfe_u32 v33, v32, 16, 1
	v_add3_u32 v32, v32, v33, s78
	v_mov_b32_e32 v33, 0x2d0
	v_mad_u32_u24 v60, v43, s76, v33
	v_add_u32_e32 v33, v67, v60
	ds_write_b16_d16_hi v33, v32 offset:32768
	v_sub_f32_e32 v33, v47, v38
	v_mul_f32_e32 v33, 0x3fb8aa3b, v33
	v_exp_f32_e32 v33, v33
	v_mul_f32_e32 v32, v26, v56
	v_mul_f32_e32 v32, v32, v33
	v_bfe_u32 v33, v32, 16, 1
	v_add3_u32 v32, v32, v33, s78
	v_mov_b32_e32 v33, 0x120
	v_mad_u32_u24 v38, v43, s76, v33
	v_add_u32_e32 v33, v67, v38
	ds_write_b16_d16_hi v33, v32 offset:32768
	v_sub_f32_e32 v33, v37, v34
	v_mul_f32_e32 v33, 0x3fb8aa3b, v33
	v_exp_f32_e32 v33, v33
	v_mul_f32_e32 v32, v30, v54
	v_mul_f32_e32 v32, v32, v33
	v_bfe_u32 v33, v32, 16, 1
	v_add3_u32 v32, v32, v33, s78
	v_mov_b32_e32 v33, 0x360
	v_mad_u32_u24 v34, v43, s76, v33
	v_add_u32_e32 v33, v67, v34
	ds_write_b16_d16_hi v33, v32 offset:32768
	v_add_u32_e32 v32, 0x7c00, v69
	ds_read2_b32 v[32:33], v32 offset0:131 offset1:135
	s_waitcnt lgkmcnt(0)
	v_sub_f32_e32 v39, v32, v39
	v_mul_f32_e32 v39, 0x3fb8aa3b, v39
	v_exp_f32_e32 v39, v39
	v_sub_f32_e32 v35, v33, v35
	v_mul_f32_e32 v35, 0x3fb8aa3b, v35
	v_exp_f32_e32 v35, v35
	v_mul_f32_e32 v39, v53, v39
	v_bfe_u32 v53, v39, 16, 1
	v_add3_u32 v39, v39, v53, s78
	v_mov_b32_e32 v53, 0x1b0
	v_mad_u32_u24 v54, v43, s76, v53
	v_add_u32_e32 v53, v67, v54
	ds_write_b16_d16_hi v53, v39 offset:32768
	v_mul_f32_e32 v39, v31, v52
	v_mul_f32_e32 v35, v39, v35
	v_bfe_u32 v39, v35, 16, 1
	v_add3_u32 v35, v35, v39, s78
	v_mov_b32_e32 v39, 0x3f0
	v_mad_u32_u24 v39, v43, s76, v39
	v_add_u32_e32 v52, v67, v39
	ds_write_b16_d16_hi v52, v35 offset:32768
	v_add_u32_e32 v35, v65, v66
	ds_write_b16 v35, v20 offset:51200
	ds_write_b16_d16_hi v35, v20 offset:51344
	ds_write_b16 v35, v21 offset:51488
	ds_write_b16_d16_hi v35, v21 offset:51632
	ds_write_b16 v35, v22 offset:51776
	ds_write_b16_d16_hi v35, v22 offset:51920
	ds_write_b16 v35, v23 offset:52064
	ds_write_b16_d16_hi v35, v23 offset:52208
	v_add_u32_e32 v20, 0x200, v42
	v_ashrrev_i32_e32 v20, 4, v20
	v_bitop3_b32 v21, v20, v51, 56 bitop3:0x78
	v_lshl_add_u32 v35, v20, 9, v50
	v_lshlrev_b32_e32 v56, 1, v21
	ds_read_b128 v[20:23], v35
	ds_read_b128 v[50:53], v35 offset:16
	v_add_u32_e32 v66, 0, v56
	s_waitcnt lgkmcnt(1)
	v_sub_f32_e32 v20, v44, v20
	v_mul_f32_e32 v20, 0x3fb8aa3b, v20
	v_exp_f32_e32 v20, v20
	v_sub_f32_e32 v21, v46, v21
	v_mul_f32_e32 v21, 0x3fb8aa3b, v21
	v_exp_f32_e32 v21, v21
	v_mul_f32_e32 v20, v24, v20
	v_bfe_u32 v24, v20, 16, 1
	v_add3_u32 v20, v20, v24, s78
	v_mad_u32_u24 v24, v43, s76, v66
	ds_write_b16_d16_hi v24, v20 offset:32768
	s_waitcnt lgkmcnt(1)
	v_sub_f32_e32 v24, v45, v50
	v_mul_f32_e32 v24, 0x3fb8aa3b, v24
	v_exp_f32_e32 v24, v24
	v_mul_f32_e32 v20, v28, v63
	v_mul_f32_e32 v20, v20, v24
	v_bfe_u32 v24, v20, 16, 1
	v_add3_u32 v20, v20, v24, s78
	v_add_u32_e32 v24, v66, v68
	ds_write_b16_d16_hi v24, v20 offset:32768
	v_mul_f32_e32 v20, v25, v62
	v_mul_f32_e32 v20, v20, v21
	v_bfe_u32 v21, v20, 16, 1
	v_add3_u32 v20, v20, v21, s78
	v_add_u32_e32 v21, v66, v70
	ds_write_b16_d16_hi v21, v20 offset:32768
	v_sub_f32_e32 v21, v36, v51
	v_mul_f32_e32 v21, 0x3fb8aa3b, v21
	v_exp_f32_e32 v21, v21
	v_mul_f32_e32 v20, v29, v61
	v_mul_f32_e32 v20, v20, v21
	v_bfe_u32 v21, v20, 16, 1
	v_add3_u32 v20, v20, v21, s78
	v_add_u32_e32 v21, v66, v60
	ds_write_b16_d16_hi v21, v20 offset:32768
	v_sub_f32_e32 v21, v47, v22
	v_mul_f32_e32 v21, 0x3fb8aa3b, v21
	v_exp_f32_e32 v21, v21
	v_mul_f32_e32 v20, v26, v59
	v_mul_f32_e32 v20, v20, v21
	v_bfe_u32 v21, v20, 16, 1
	v_add3_u32 v20, v20, v21, s78
	v_add_u32_e32 v21, v66, v38
	ds_write_b16_d16_hi v21, v20 offset:32768
	v_sub_f32_e32 v21, v37, v52
	v_mul_f32_e32 v21, 0x3fb8aa3b, v21
	v_exp_f32_e32 v21, v21
	v_mul_f32_e32 v20, v30, v58
	v_mul_f32_e32 v20, v20, v21
	v_bfe_u32 v21, v20, 16, 1
	v_add3_u32 v20, v20, v21, s78
	v_add_u32_e32 v21, v66, v34
	ds_write_b16_d16_hi v21, v20 offset:32768
	v_sub_f32_e32 v21, v32, v23
	v_mul_f32_e32 v21, 0x3fb8aa3b, v21
	v_exp_f32_e32 v21, v21
	v_mul_f32_e32 v20, v27, v57
	v_mul_f32_e32 v20, v20, v21
	v_bfe_u32 v21, v20, 16, 1
	v_add3_u32 v20, v20, v21, s78
	v_add_u32_e32 v21, v66, v54
	ds_write_b16_d16_hi v21, v20 offset:32768
	v_sub_f32_e32 v21, v33, v53
	v_mul_f32_e32 v21, 0x3fb8aa3b, v21
	v_exp_f32_e32 v21, v21
	v_mul_f32_e32 v20, v31, v55
	v_mul_f32_e32 v20, v20, v21
	v_bfe_u32 v21, v20, 16, 1
	v_add3_u32 v20, v20, v21, s78
	v_add_u32_e32 v21, v66, v39
	ds_write_b16_d16_hi v21, v20 offset:32768
	v_add_u32_e32 v20, v65, v56
	ds_write_b16 v20, v16 offset:51200
	ds_write_b16_d16_hi v20, v16 offset:51344
	ds_write_b16 v20, v17 offset:51488
	ds_write_b16_d16_hi v20, v17 offset:51632
	ds_write_b16 v20, v18 offset:51776
	ds_write_b16_d16_hi v20, v18 offset:51920
	ds_write_b16 v20, v19 offset:52064
	ds_write_b16_d16_hi v20, v19 offset:52208
	s_and_saveexec_b64 s[2:3], s[38:39]
	s_cbranch_execz .LBB0_541
	v_lshl_add_u32 v16, v42, 2, 0
	ds_read_b32 v16, v16 offset:32256
	s_waitcnt lgkmcnt(0)
	v_mul_f32_e32 v16, 0x3fb8aa3b, v16
	v_exp_f32_e32 v18, v16
	v_lshl_add_u32 v16, s22, 7, v42
	v_ashrrev_i32_e32 v17, 31, v16
	v_lshl_add_u64 v[16:17], v[16:17], 2, s[16:17]
	global_store_dword v[16:17], v18, off

; __device__ __forceinline__ void unpack8(const u32x4& w, f32x4& v0, f32x4& v1) { v0[0] = bflo(w.x); v0[1] = bfhi(w.x); v0[2] = bflo(w.y); v0[3] = bfhi(w.y); v1[0] = bflo(w.z); v1[1] = bfhi(w.z); v1[2] = bflo(w.w); v1[3] = bfhi(w.w); }
; __device__ __forceinline__ void hg_cum(const u32x4 (&ev)[2], int l, int h, const float* hlb, float* cumS, float* lbS, int tid) {
;     ...
; #pragma unroll
;     for (int q = 0; q < 2; ++q) {
;         const int idx = tid + 512 * q, t = idx >> 4, k8 = (idx & 15) * 8;
;         f32x4 a, bb; unpack8(ev[q], a, bb);
;         const f32x4 l0 = *(const f32x4*)(lbS + k8), l1 = *(const f32x4*)(lbS + k8 + 4);
; #pragma unroll
;         for (int j = 0; j < 4; ++j) { a[j] = __logf(fmaxf(1.0f - l0[j] * a[j], 1e-30f)); bb[j] = __logf(fmaxf(1.0f - l1[j] * bb[j], 1e-30f)); }
;         *(f32x4*)(cumS + t * 128 + k8) = a; *(f32x4*)(cumS + t * 128 + k8 + 4) = bb;
.LBB0_824:
	s_or_b64 exec, exec, s[2:3]
	v_lshl_add_u32 v48, v65, 2, 0
	v_add_u32_e32 v69, 0x1bc00, v48
	s_waitcnt lgkmcnt(0)
	s_barrier
	s_waitcnt vmcnt(4)
	v_lshlrev_b32_e32 v54, 16, v38
	v_and_b32_e32 v55, 0xffff0000, v38
	v_lshlrev_b32_e32 v50, 16, v39
	v_and_b32_e32 v51, 0xffff0000, v39
	ds_read_b128 v[58:61], v69
	ds_read_b128 v[38:41], v69 offset:16
	v_lshlrev_b32_e32 v56, 16, v36
	v_and_b32_e32 v57, 0xffff0000, v36
	v_lshlrev_b32_e32 v52, 16, v37
	s_waitcnt lgkmcnt(1)
	v_fma_f32 v36, -v58, v56, 1.0
	v_max_f32_e32 v36, 0xda24260, v36
	v_cmp_gt_f32_e32 vcc, s33, v36
	v_and_b32_e32 v53, 0xffff0000, v37
	s_waitcnt lgkmcnt(0)
	v_fma_f32 v38, -v38, v54, 1.0
	v_cndmask_b32_e64 v37, 0, 32, vcc
	v_ldexp_f32 v36, v36, v37
	v_log_f32_e32 v36, v36
	v_max_f32_e32 v38, 0xda24260, v38
	v_fma_f32 v40, -v40, v50, 1.0
	v_max_f32_e32 v40, 0xda24260, v40
	v_mul_f32_e32 v37, 0x3f317217, v36
	v_fma_f32 v37, v36, s79, -v37
	v_fmac_f32_e32 v37, 0x3377d1cf, v36
	v_fmac_f32_e32 v37, 0x3f317217, v36
	v_cmp_lt_f32_e64 s[40:41], |v36|, s80
	s_waitcnt vmcnt(1)
	v_lshlrev_b32_e32 v62, 16, v32
	v_and_b32_e32 v63, 0xffff0000, v32
	v_cndmask_b32_e64 v36, v36, v37, s[40:41]
	v_cndmask_b32_e32 v37, 0, v212, vcc
	v_sub_f32_e32 v36, v36, v37
	v_fma_f32 v37, -v59, v57, 1.0
	v_max_f32_e32 v37, 0xda24260, v37
	v_cmp_gt_f32_e32 vcc, s33, v37
	v_ashrrev_i32_e32 v47, 31, v46
	v_ashrrev_i32_e32 v45, 31, v44
	v_cndmask_b32_e64 v58, 0, 32, vcc
	v_ldexp_f32 v37, v37, v58
	v_log_f32_e32 v37, v37
	s_nop 0
	v_mul_f32_e32 v58, 0x3f317217, v37
	v_fma_f32 v58, v37, s79, -v58
	v_fmac_f32_e32 v58, 0x3377d1cf, v37
	v_fmac_f32_e32 v58, 0x3f317217, v37
	v_cmp_lt_f32_e64 s[40:41], |v37|, s80
	s_nop 1
	v_cndmask_b32_e64 v37, v37, v58, s[40:41]
	v_cndmask_b32_e32 v58, 0, v212, vcc
	v_cmp_gt_f32_e32 vcc, s33, v38
	v_sub_f32_e32 v37, v37, v58
	s_nop 0
	v_cndmask_b32_e64 v58, 0, 32, vcc
	v_ldexp_f32 v38, v38, v58
	v_log_f32_e32 v38, v38
	s_nop 0
	v_mul_f32_e32 v58, 0x3f317217, v38
	v_fma_f32 v58, v38, s79, -v58
	v_fmac_f32_e32 v58, 0x3377d1cf, v38
	v_fmac_f32_e32 v58, 0x3f317217, v38
	v_cmp_lt_f32_e64 s[40:41], |v38|, s80
	s_nop 1
	v_cndmask_b32_e64 v38, v38, v58, s[40:41]
	v_cndmask_b32_e32 v58, 0, v212, vcc
	v_sub_f32_e32 v58, v38, v58
	v_fma_f32 v38, -v39, v55, 1.0
	v_max_f32_e32 v38, 0xda24260, v38
	v_cmp_gt_f32_e32 vcc, s33, v38
	s_nop 1
	v_cndmask_b32_e64 v39, 0, 32, vcc
	v_ldexp_f32 v38, v38, v39
	v_log_f32_e32 v38, v38
	s_nop 0
	v_mul_f32_e32 v39, 0x3f317217, v38
	v_fma_f32 v39, v38, s79, -v39
	v_fmac_f32_e32 v39, 0x3377d1cf, v38
	v_fmac_f32_e32 v39, 0x3f317217, v38
	v_cmp_lt_f32_e64 s[40:41], |v38|, s80
	s_nop 1
	v_cndmask_b32_e64 v38, v38, v39, s[40:41]
	v_cndmask_b32_e32 v39, 0, v212, vcc
	v_sub_f32_e32 v59, v38, v39
	v_fma_f32 v38, -v60, v52, 1.0
	v_max_f32_e32 v38, 0xda24260, v38
	v_cmp_gt_f32_e32 vcc, s33, v38
	s_nop 1
	v_cndmask_b32_e64 v39, 0, 32, vcc
	v_ldexp_f32 v38, v38, v39
	v_log_f32_e32 v38, v38
	s_nop 0
	v_mul_f32_e32 v39, 0x3f317217, v38
	v_fma_f32 v39, v38, s79, -v39
	v_fmac_f32_e32 v39, 0x3377d1cf, v38
	v_fmac_f32_e32 v39, 0x3f317217, v38
	v_cmp_lt_f32_e64 s[40:41], |v38|, s80
	s_nop 1
	v_cndmask_b32_e64 v38, v38, v39, s[40:41]
	v_cndmask_b32_e32 v39, 0, v212, vcc
	v_sub_f32_e32 v38, v38, v39
	v_fma_f32 v39, -v61, v53, 1.0
	v_max_f32_e32 v39, 0xda24260, v39
	v_cmp_gt_f32_e32 vcc, s33, v39
	s_nop 1
	v_cndmask_b32_e64 v60, 0, 32, vcc
	v_ldexp_f32 v39, v39, v60
	v_log_f32_e32 v39, v39
	s_nop 0
	v_mul_f32_e32 v60, 0x3f317217, v39
	v_fma_f32 v60, v39, s79, -v60
	v_fmac_f32_e32 v60, 0x3377d1cf, v39
	v_fmac_f32_e32 v60, 0x3f317217, v39
	v_cmp_lt_f32_e64 s[40:41], |v39|, s80
	s_nop 1
	v_cndmask_b32_e64 v39, v39, v60, s[40:41]
	v_cndmask_b32_e32 v60, 0, v212, vcc
	v_cmp_gt_f32_e32 vcc, s33, v40
	v_sub_f32_e32 v39, v39, v60
	s_nop 0
	v_cndmask_b32_e64 v60, 0, 32, vcc
	v_ldexp_f32 v40, v40, v60
	v_log_f32_e32 v40, v40
	s_nop 0
	v_mul_f32_e32 v60, 0x3f317217, v40
	v_fma_f32 v60, v40, s79, -v60
	v_fmac_f32_e32 v60, 0x3377d1cf, v40
	v_fmac_f32_e32 v60, 0x3f317217, v40
	v_cmp_lt_f32_e64 s[40:41], |v40|, s80
	s_nop 1
	v_cndmask_b32_e64 v40, v40, v60, s[40:41]
	v_cndmask_b32_e32 v60, 0, v212, vcc
	v_sub_f32_e32 v60, v40, v60
	v_fma_f32 v40, -v41, v51, 1.0
	v_max_f32_e32 v40, 0xda24260, v40
	v_cmp_gt_f32_e32 vcc, s33, v40
	s_nop 1
	v_cndmask_b32_e64 v41, 0, 32, vcc
	v_ldexp_f32 v40, v40, v41
	v_log_f32_e32 v40, v40
	s_nop 0
	v_mul_f32_e32 v41, 0x3f317217, v40
	v_fma_f32 v41, v40, s79, -v41
	v_fmac_f32_e32 v41, 0x3377d1cf, v40
	v_fmac_f32_e32 v41, 0x3f317217, v40
	v_cmp_lt_f32_e64 s[40:41], |v40|, s80
	s_nop 1
	v_cndmask_b32_e64 v40, v40, v41, s[40:41]
	v_cndmask_b32_e32 v41, 0, v212, vcc
	v_sub_f32_e32 v61, v40, v41
	v_and_b32_e32 v40, 0x3fffff80, v68
	v_lshl_add_u32 v70, v40, 2, v48
	ds_write_b128 v70, v[36:39]
	ds_write_b128 v70, v[58:61] offset:16
	v_lshlrev_b32_e32 v58, 16, v33
	v_and_b32_e32 v59, 0xffff0000, v33
	v_lshlrev_b32_e32 v60, 16, v34
	v_and_b32_e32 v61, 0xffff0000, v34
	v_lshlrev_b32_e32 v40, 16, v35
	v_and_b32_e32 v41, 0xffff0000, v35
	ds_read_b128 v[36:39], v69
	ds_read_b128 v[32:35], v69 offset:16
	s_waitcnt lgkmcnt(1)
	v_fma_f32 v36, -v36, v62, 1.0
	v_max_f32_e32 v36, 0xda24260, v36
	v_cmp_gt_f32_e32 vcc, s33, v36
	v_fma_f32 v37, -v37, v63, 1.0
	v_max_f32_e32 v37, 0xda24260, v37
	v_cndmask_b32_e64 v71, 0, 32, vcc
	v_ldexp_f32 v36, v36, v71
	v_log_f32_e32 v36, v36
	s_waitcnt lgkmcnt(0)
; __device__ __forceinline__ void unpack8(const u32x4& w, f32x4& v0, f32x4& v1) { v0[0] = bflo(w.x); v0[1] = bfhi(w.x); v0[2] = bflo(w.y); v0[3] = bfhi(w.y); v1[0] = bflo(w.z); v1[1] = bfhi(w.z); v1[2] = bflo(w.w); v1[3] = bfhi(w.w); }
; __device__ __forceinline__ void hg_cum(const u32x4 (&ev)[2], int l, int h, const float* hlb, float* cumS, float* lbS, int tid) {
;     ...
;         const int idx = tid + 512 * q, t = idx >> 4, k8 = (idx & 15) * 8;
;         f32x4 a, bb; unpack8(ev[q], a, bb);
;         const f32x4 l0 = *(const f32x4*)(lbS + k8), l1 = *(const f32x4*)(lbS + k8 + 4);
; #pragma unroll
;         for (int j = 0; j < 4; ++j) { a[j] = __logf(fmaxf(1.0f - l0[j] * a[j], 1e-30f)); bb[j] = __logf(fmaxf(1.0f - l1[j] * bb[j], 1e-30f)); }
;         *(f32x4*)(cumS + t * 128 + k8) = a; *(f32x4*)(cumS + t * 128 + k8 + 4) = bb;
;     }
;     __syncthreads();
;     const int k = tid & 127, seg = tid >> 7;
;     { float run = 0.f;
; #pragma unroll
;       for (int tt = 0; tt < 16; ++tt) { const int t = seg * 16 + tt; run += cumS[t * 128 + k]; cumS[t * 128 + k] = run; } }
;     __syncthreads();
;     float off = 0.f;
;     for (int sp = 0; sp < seg; ++sp) off += cumS[(16 * sp + 15) * 128 + k];
	v_fma_f32 v32, -v32, v60, 1.0
	v_max_f32_e32 v32, 0xda24260, v32
	v_fma_f32 v33, -v33, v61, 1.0
	v_mul_f32_e32 v71, 0x3f317217, v36
	v_fma_f32 v71, v36, s79, -v71
	v_fmac_f32_e32 v71, 0x3377d1cf, v36
	v_fmac_f32_e32 v71, 0x3f317217, v36
	v_cmp_lt_f32_e64 s[40:41], |v36|, s80
	v_max_f32_e32 v33, 0xda24260, v33
	v_fma_f32 v38, -v38, v58, 1.0
	v_cndmask_b32_e64 v36, v36, v71, s[40:41]
	v_cndmask_b32_e32 v71, 0, v212, vcc
	v_cmp_gt_f32_e32 vcc, s33, v37
	v_sub_f32_e32 v36, v36, v71
	v_max_f32_e32 v38, 0xda24260, v38
	v_cndmask_b32_e64 v71, 0, 32, vcc
	v_ldexp_f32 v37, v37, v71
	v_log_f32_e32 v37, v37
	v_fma_f32 v39, -v39, v59, 1.0
	v_max_f32_e32 v39, 0xda24260, v39
	v_fma_f32 v34, -v34, v40, 1.0
	v_mul_f32_e32 v71, 0x3f317217, v37
	v_fma_f32 v71, v37, s79, -v71
	v_fmac_f32_e32 v71, 0x3377d1cf, v37
	v_fmac_f32_e32 v71, 0x3f317217, v37
	v_cmp_lt_f32_e64 s[40:41], |v37|, s80
	v_max_f32_e32 v34, 0xda24260, v34
	v_fma_f32 v35, -v35, v41, 1.0
	v_cndmask_b32_e64 v37, v37, v71, s[40:41]
	v_cndmask_b32_e32 v71, 0, v212, vcc
	v_cmp_gt_f32_e32 vcc, s33, v32
	v_sub_f32_e32 v37, v37, v71
	v_max_f32_e32 v35, 0xda24260, v35
	v_cndmask_b32_e64 v71, 0, 32, vcc
	v_ldexp_f32 v32, v32, v71
	v_log_f32_e32 v32, v32
	s_nop 0
	v_mul_f32_e32 v71, 0x3f317217, v32
	v_fma_f32 v71, v32, s79, -v71
	v_fmac_f32_e32 v71, 0x3377d1cf, v32
	v_fmac_f32_e32 v71, 0x3f317217, v32
	v_cmp_lt_f32_e64 s[40:41], |v32|, s80
	s_nop 1
	v_cndmask_b32_e64 v32, v32, v71, s[40:41]
	v_cndmask_b32_e32 v71, 0, v212, vcc
	v_cmp_gt_f32_e32 vcc, s33, v33
	v_sub_f32_e32 v32, v32, v71
	s_nop 0
	v_cndmask_b32_e64 v71, 0, 32, vcc
	v_ldexp_f32 v33, v33, v71
	v_log_f32_e32 v33, v33
	s_nop 0
	v_mul_f32_e32 v71, 0x3f317217, v33
	v_fma_f32 v71, v33, s79, -v71
	v_fmac_f32_e32 v71, 0x3377d1cf, v33
	v_fmac_f32_e32 v71, 0x3f317217, v33
	v_cmp_lt_f32_e64 s[40:41], |v33|, s80
	s_nop 1
	v_cndmask_b32_e64 v33, v33, v71, s[40:41]
	v_cndmask_b32_e32 v71, 0, v212, vcc
	v_cmp_gt_f32_e32 vcc, s33, v38
	v_sub_f32_e32 v33, v33, v71
	s_nop 0
	v_cndmask_b32_e64 v71, 0, 32, vcc
	v_ldexp_f32 v38, v38, v71
	v_log_f32_e32 v38, v38
	s_nop 0
	v_mul_f32_e32 v71, 0x3f317217, v38
	v_fma_f32 v71, v38, s79, -v71
	v_fmac_f32_e32 v71, 0x3377d1cf, v38
	v_fmac_f32_e32 v71, 0x3f317217, v38
	v_cmp_lt_f32_e64 s[40:41], |v38|, s80
	s_nop 1
	v_cndmask_b32_e64 v38, v38, v71, s[40:41]
	v_cndmask_b32_e32 v71, 0, v212, vcc
	v_cmp_gt_f32_e32 vcc, s33, v39
	v_sub_f32_e32 v38, v38, v71
	s_nop 0
	v_cndmask_b32_e64 v71, 0, 32, vcc
	v_ldexp_f32 v39, v39, v71
	v_log_f32_e32 v39, v39
	s_nop 0
	v_mul_f32_e32 v71, 0x3f317217, v39
	v_fma_f32 v71, v39, s79, -v71
	v_fmac_f32_e32 v71, 0x3377d1cf, v39
	v_fmac_f32_e32 v71, 0x3f317217, v39
	v_cmp_lt_f32_e64 s[40:41], |v39|, s80
	s_nop 1
	v_cndmask_b32_e64 v39, v39, v71, s[40:41]
	v_cndmask_b32_e32 v71, 0, v212, vcc
	v_cmp_gt_f32_e32 vcc, s33, v34
	v_sub_f32_e32 v39, v39, v71
	s_nop 0
	v_cndmask_b32_e64 v71, 0, 32, vcc
	v_ldexp_f32 v34, v34, v71
	v_log_f32_e32 v34, v34
	s_nop 0
	v_mul_f32_e32 v71, 0x3f317217, v34
	v_fma_f32 v71, v34, s79, -v71
	v_fmac_f32_e32 v71, 0x3377d1cf, v34
	v_fmac_f32_e32 v71, 0x3f317217, v34
	v_cmp_lt_f32_e64 s[40:41], |v34|, s80
	s_nop 1
	v_cndmask_b32_e64 v34, v34, v71, s[40:41]
	v_cndmask_b32_e32 v71, 0, v212, vcc
	v_cmp_gt_f32_e32 vcc, s33, v35
	v_sub_f32_e32 v34, v34, v71
	s_nop 0
	v_cndmask_b32_e64 v71, 0, 32, vcc
	v_ldexp_f32 v35, v35, v71
	v_log_f32_e32 v35, v35
	s_nop 0
	v_mul_f32_e32 v71, 0x3f317217, v35
	v_fma_f32 v71, v35, s79, -v71
	v_fmac_f32_e32 v71, 0x3377d1cf, v35
	v_fmac_f32_e32 v71, 0x3f317217, v35
	v_cmp_lt_f32_e64 s[40:41], |v35|, s80
	s_nop 1
	v_cndmask_b32_e64 v35, v35, v71, s[40:41]
	v_cndmask_b32_e32 v71, 0, v212, vcc
	v_sub_f32_e32 v35, v35, v71
	ds_write_b128 v70, v[36:39] offset:16384
	ds_write_b128 v70, v[32:35] offset:16400
	v_and_b32_e32 v35, 0x7f, v67
	v_ashrrev_i32_e32 v34, 7, v67
	v_lshlrev_b32_e32 v32, 13, v34
	v_lshlrev_b32_e32 v33, 2, v35
	v_add3_u32 v32, 0, v32, v33
	s_waitcnt lgkmcnt(0)
	s_barrier
	ds_read2st64_b32 v[104:105], v32 offset1:2
	ds_read2st64_b32 v[106:107], v32 offset0:4 offset1:6
	ds_read2st64_b32 v[108:109], v32 offset0:8 offset1:10
	ds_read2st64_b32 v[110:111], v32 offset0:12 offset1:14
	ds_read2st64_b32 v[112:113], v32 offset0:16 offset1:18
	ds_read2st64_b32 v[114:115], v32 offset0:20 offset1:22
	ds_read2st64_b32 v[116:117], v32 offset0:24 offset1:26
	ds_read2st64_b32 v[118:119], v32 offset0:28 offset1:30
	v_cmp_lt_i32_e32 vcc, 0, v34
	s_waitcnt lgkmcnt(7)
	v_add_f32_e32 v104, 0, v104
	v_add_f32_e32 v105, v104, v105
	ds_write2st64_b32 v32, v104, v105 offset1:2
	s_waitcnt lgkmcnt(7)
	v_add_f32_e32 v106, v105, v106
	v_add_f32_e32 v107, v106, v107
	ds_write2st64_b32 v32, v106, v107 offset0:4 offset1:6
	s_waitcnt lgkmcnt(7)
	v_add_f32_e32 v108, v107, v108
	v_add_f32_e32 v109, v108, v109
	ds_write2st64_b32 v32, v108, v109 offset0:8 offset1:10
	s_waitcnt lgkmcnt(7)
	v_add_f32_e32 v110, v109, v110
	v_add_f32_e32 v111, v110, v111
	ds_write2st64_b32 v32, v110, v111 offset0:12 offset1:14
	s_waitcnt lgkmcnt(7)
	v_add_f32_e32 v112, v111, v112
	v_add_f32_e32 v113, v112, v113
	ds_write2st64_b32 v32, v112, v113 offset0:16 offset1:18
	s_waitcnt lgkmcnt(7)
	v_add_f32_e32 v114, v113, v114
	v_add_f32_e32 v115, v114, v115
	ds_write2st64_b32 v32, v114, v115 offset0:20 offset1:22
	s_waitcnt lgkmcnt(7)
	v_add_f32_e32 v116, v115, v116
	v_add_f32_e32 v117, v116, v117
	ds_write2st64_b32 v32, v116, v117 offset0:24 offset1:26
	s_waitcnt lgkmcnt(7)
	v_add_f32_e32 v33, v117, v118
	v_add_f32_e32 v36, v33, v119
	ds_write2st64_b32 v32, v33, v36 offset0:28 offset1:30
	v_mov_b32_e32 v33, 0
	s_waitcnt lgkmcnt(0)
	s_barrier
	s_and_saveexec_b64 s[2:3], vcc
	s_cbranch_execz .LBB0_828
	v_lshl_add_u32 v35, v35, 2, s60
	v_mov_b32_e32 v33, 0
	s_mov_b64 s[34:35], 0

; __device__ __forceinline__ u32x4 pack8(const f32x4& v0, const f32x4& v1) { u32x4 w; w.x = cvt_pk_bf16(v0[0], v0[1]); w.y = cvt_pk_bf16(v0[2], v0[3]); w.z = cvt_pk_bf16(v1[0], v1[1]); w.w = cvt_pk_bf16(v1[2], v1[3]); return w; }
; __device__ __forceinline__ void unpack8(const u32x4& w, f32x4& v0, f32x4& v1) { v0[0] = bflo(w.x); v0[1] = bfhi(w.x); v0[2] = bflo(w.y); v0[3] = bfhi(w.y); v1[0] = bflo(w.z); v1[1] = bfhi(w.z); v1[2] = bflo(w.w); v1[3] = bfhi(w.w); }
; __device__ __forceinline__ void hg_cum(const u32x4 (&ev)[2], int l, int h, const float* hlb, float* cumS, float* lbS, int tid) {
;     ...
;     __syncthreads();
; #pragma unroll
;     for (int tt = 0; tt < 16; ++tt) cumS[(seg * 16 + tt) * 128 + k] += off;
;     __syncthreads();
; __device__ __forceinline__ void hgC_item(const Bufs& B, int l, int it, unsigned char* shm, const float* hlb, const float* hn) {
;     ...
;     for (int q = 0; q < 2; ++q) {
;         const int idx = tid + 512 * q, t = idx >> 4, k8 = (idx & 15) * 8;
;         f32x4 q0, q1, e0, e1; unpack8(qv[q], q0, q1); unpack8(ev[q], e0, e1);
;         const u32x4 iw = iv[q];
;         const int tx = t ^ (((k8 >> 3) & 7) << 3);
;         const f32x4 c0 = *(const f32x4*)(cumS + t * 128 + k8), c1 = *(const f32x4*)(cumS + t * 128 + k8 + 4), m0v = *(const f32x4*)(cumS + 31 * 128 + k8), m1v = *(const f32x4*)(cumS + 31 * 128 + k8 + 4);
;         const f32x4 l0 = *(const f32x4*)(lbS + k8), l1 = *(const f32x4*)(lbS + k8 + 4);
;         f32x4 x0, x1, y0, y1, z0, z1;
; #pragma unroll
;         for (int j = 0; j < 4; ++j) {
;             x0[j] = q0[j] * __expf(c0[j]); x1[j] = q1[j] * __expf(c1[j]);
;             y0[j] = q0[j] * __expf(fminf(c0[j] - m0v[j], 80.f)); y1[j] = q1[j] * __expf(fminf(c1[j] - m1v[j], 80.f));
;             z0[j] = l0[j] * e0[j] * __expf(fminf(m0v[j] - c0[j], 80.f)); z1[j] = l1[j] * e1[j] * __expf(fminf(m1v[j] - c1[j], 80.f));
;         }
;         *(u32x4*)(qe + t * 136 + k8) = pack8(x0, x1); *(u32x4*)(qa + t * 136 + k8) = pack8(y0, y1); *(u32x4*)(kb + t * 136 + k8) = pack8(z0, z1);
.LBB0_828:
	s_or_b64 exec, exec, s[2:3]
	s_barrier
	ds_read2st64_b32 v[104:105], v32 offset1:2
	ds_read2st64_b32 v[106:107], v32 offset0:4 offset1:6
	ds_read2st64_b32 v[108:109], v32 offset0:8 offset1:10
	ds_read2st64_b32 v[110:111], v32 offset0:12 offset1:14
	ds_read2st64_b32 v[112:113], v32 offset0:16 offset1:18
	ds_read2st64_b32 v[114:115], v32 offset0:20 offset1:22
	ds_read2st64_b32 v[116:117], v32 offset0:24 offset1:26
	ds_read2st64_b32 v[118:119], v32 offset0:28 offset1:30
	v_lshlrev_b32_e32 v38, 16, v28
	v_and_b32_e32 v39, 0xffff0000, v28
	v_lshlrev_b32_e32 v86, 16, v29
	v_and_b32_e32 v87, 0xffff0000, v29
	v_lshlrev_b32_e32 v88, 16, v30
	v_and_b32_e32 v89, 0xffff0000, v30
	v_lshlrev_b32_e32 v90, 16, v31
	v_and_b32_e32 v91, 0xffff0000, v31
	v_sub_u32_e32 v100, v48, v42
	v_cmp_gt_i32_e32 vcc, 16, v66
	s_waitcnt lgkmcnt(7)
	v_add_f32_e32 v104, v33, v104
	v_add_f32_e32 v105, v33, v105
	ds_write2st64_b32 v32, v104, v105 offset1:2
	s_waitcnt lgkmcnt(7)
	v_add_f32_e32 v106, v33, v106
	v_add_f32_e32 v107, v33, v107
	ds_write2st64_b32 v32, v106, v107 offset0:4 offset1:6
	s_waitcnt lgkmcnt(7)
	v_add_f32_e32 v108, v33, v108
	v_add_f32_e32 v109, v33, v109
	ds_write2st64_b32 v32, v108, v109 offset0:8 offset1:10
	s_waitcnt lgkmcnt(7)
	v_add_f32_e32 v110, v33, v110
	v_add_f32_e32 v111, v33, v111
	ds_write2st64_b32 v32, v110, v111 offset0:12 offset1:14
	s_waitcnt lgkmcnt(7)
	v_add_f32_e32 v112, v33, v112
	v_add_f32_e32 v113, v33, v113
	ds_write2st64_b32 v32, v112, v113 offset0:16 offset1:18
	s_waitcnt lgkmcnt(7)
	v_add_f32_e32 v114, v33, v114
	v_add_f32_e32 v115, v33, v115
	ds_write2st64_b32 v32, v114, v115 offset0:20 offset1:22
	s_waitcnt lgkmcnt(7)
	v_add_f32_e32 v116, v33, v116
	v_add_f32_e32 v117, v33, v117
	ds_write2st64_b32 v32, v116, v117 offset0:24 offset1:26
	s_waitcnt lgkmcnt(7)
	v_add_f32_e32 v34, v33, v118
	v_add_f32_e32 v33, v33, v119
	ds_write2st64_b32 v32, v34, v33 offset0:28 offset1:30
	v_lshl_add_u32 v34, v43, 9, v48
	s_waitcnt lgkmcnt(0)
	s_barrier
	ds_read_b128 v[28:31], v34
	ds_read_b128 v[34:37], v34 offset:16
	ds_read_b128 v[70:73], v48 offset:15872
	ds_read_b128 v[74:77], v48 offset:15888
	ds_read_b128 v[78:81], v69
	ds_read_b128 v[82:85], v69 offset:16
	s_waitcnt lgkmcnt(4)
	v_mul_f32_e32 v93, 0x3fb8aa3b, v34
	v_exp_f32_e32 v94, v93
	s_waitcnt lgkmcnt(3)
	v_sub_f32_e32 v93, v28, v70
	v_min_f32_e32 v93, 0x42a00000, v93
	v_mul_f32_e32 v93, 0x3fb8aa3b, v93
	v_exp_f32_e32 v96, v93
	s_waitcnt lgkmcnt(2)
	v_sub_f32_e32 v93, v34, v74
	v_min_f32_e32 v93, 0x42a00000, v93
	v_mul_f32_e32 v92, 0x3fb8aa3b, v28
	v_mul_f32_e32 v93, 0x3fb8aa3b, v93
	v_sub_f32_e32 v28, v70, v28
	v_mul_f32_e32 v70, 0x3fb8aa3b, v29
	v_exp_f32_e32 v98, v93
	v_exp_f32_e32 v93, v70
	v_mul_f32_e32 v70, 0x3fb8aa3b, v35
	v_exp_f32_e32 v95, v70
	v_sub_f32_e32 v70, v29, v71
	v_sub_f32_e32 v29, v71, v29
	v_min_f32_e32 v28, 0x42a00000, v28
	v_min_f32_e32 v29, 0x42a00000, v29
	v_mul_f32_e32 v28, 0x3fb8aa3b, v28
	v_mul_f32_e32 v29, 0x3fb8aa3b, v29
	v_exp_f32_e32 v28, v28
	v_exp_f32_e32 v29, v29
	s_waitcnt lgkmcnt(1)
	v_pk_mul_f32 v[56:57], v[78:79], v[56:57]
	v_sub_f32_e32 v34, v74, v34
	v_min_f32_e32 v34, 0x42a00000, v34
	v_pk_mul_f32 v[56:57], v[56:57], v[28:29]
	v_sub_f32_e32 v28, v75, v35
	v_min_f32_e32 v70, 0x42a00000, v70
	v_min_f32_e32 v28, 0x42a00000, v28
	v_mul_f32_e32 v34, 0x3fb8aa3b, v34
	v_mul_f32_e32 v70, 0x3fb8aa3b, v70
	v_mul_f32_e32 v28, 0x3fb8aa3b, v28
	v_exp_f32_e32 v34, v34
	v_exp_f32_e32 v97, v70
	v_sub_f32_e32 v70, v35, v75
	v_exp_f32_e32 v35, v28
	s_waitcnt lgkmcnt(0)
	v_pk_mul_f32 v[28:29], v[82:83], v[54:55]
	v_min_f32_e32 v70, 0x42a00000, v70
	v_mul_f32_e32 v70, 0x3fb8aa3b, v70
	v_pk_mul_f32 v[34:35], v[28:29], v[34:35]
	v_mul_f32_e32 v29, 0x3fb8aa3b, v36
	v_exp_f32_e32 v54, v29
	v_sub_f32_e32 v29, v30, v72
	v_min_f32_e32 v29, 0x42a00000, v29
	v_mul_f32_e32 v29, 0x3fb8aa3b, v29
	v_exp_f32_e32 v99, v70
	v_exp_f32_e32 v70, v29
	v_sub_f32_e32 v29, v36, v76
	v_min_f32_e32 v29, 0x42a00000, v29
	v_mul_f32_e32 v29, 0x3fb8aa3b, v29
	v_exp_f32_e32 v74, v29
	v_sub_f32_e32 v29, v72, v30
	v_min_f32_e32 v29, 0x42a00000, v29
	v_mul_f32_e32 v29, 0x3fb8aa3b, v29
	v_mul_f32_e32 v28, 0x3fb8aa3b, v30
	v_exp_f32_e32 v30, v29
	v_sub_f32_e32 v29, v76, v36
	v_min_f32_e32 v29, 0x42a00000, v29
	v_mul_f32_e32 v29, 0x3fb8aa3b, v29
	v_exp_f32_e32 v36, v29
	v_mul_f32_e32 v29, 0x3fb8aa3b, v31
	v_exp_f32_e32 v28, v28
	v_exp_f32_e32 v29, v29
	v_sub_f32_e32 v71, v31, v73
	v_exp_f32_e32 v92, v92
	v_mul_f32_e32 v55, 0x3fb8aa3b, v37
	v_pk_mul_f32 v[78:79], v[28:29], v[86:87]
	v_sub_f32_e32 v28, v37, v77
	v_min_f32_e32 v28, 0x42a00000, v28
	v_mul_f32_e32 v28, 0x3fb8aa3b, v28
	v_exp_f32_e32 v75, v28
	v_sub_f32_e32 v28, v73, v31
	v_min_f32_e32 v28, 0x42a00000, v28
	v_mul_f32_e32 v28, 0x3fb8aa3b, v28
	v_exp_f32_e32 v31, v28
	v_pk_mul_f32 v[28:29], v[80:81], v[52:53]
	v_min_f32_e32 v71, 0x42a00000, v71
	v_exp_f32_e32 v55, v55
	v_pk_mul_f32 v[52:53], v[28:29], v[30:31]
	v_sub_f32_e32 v28, v77, v37
	v_min_f32_e32 v28, 0x42a00000, v28
	v_mul_f32_e32 v28, 0x3fb8aa3b, v28
	v_mul_f32_e32 v71, 0x3fb8aa3b, v71
	v_exp_f32_e32 v37, v28
	v_exp_f32_e32 v71, v71
	v_pk_mul_f32 v[96:97], v[96:97], v[38:39]
	v_pk_mul_f32 v[38:39], v[92:93], v[38:39]
	v_pk_mul_f32 v[28:29], v[84:85], v[50:51]
	v_pk_mul_f32 v[92:93], v[98:99], v[88:89]
	v_pk_mul_f32 v[88:89], v[94:95], v[88:89]
	v_pk_mul_f32 v[54:55], v[54:55], v[90:91]
	v_pk_mul_f32 v[36:37], v[28:29], v[36:37]
	v_cvt_pk_bf16_f32 v28, v38, v39
	v_mul_lo_u32 v38, v43, s77
	v_pk_mul_f32 v[70:71], v[70:71], v[86:87]
	v_pk_mul_f32 v[74:75], v[74:75], v[90:91]
	v_cvt_pk_bf16_f32 v29, v78, v79
	v_cvt_pk_bf16_f32 v30, v88, v89
	v_cvt_pk_bf16_f32 v31, v54, v55
; __device__ __forceinline__ u32x4 pack8(const f32x4& v0, const f32x4& v1) { u32x4 w; w.x = cvt_pk_bf16(v0[0], v0[1]); w.y = cvt_pk_bf16(v0[2], v0[3]); w.z = cvt_pk_bf16(v1[0], v1[1]); w.w = cvt_pk_bf16(v1[2], v1[3]); return w; }
; __device__ __forceinline__ void unpack8(const u32x4& w, f32x4& v0, f32x4& v1) { v0[0] = bflo(w.x); v0[1] = bfhi(w.x); v0[2] = bflo(w.y); v0[3] = bfhi(w.y); v1[0] = bflo(w.z); v1[1] = bfhi(w.z); v1[2] = bflo(w.w); v1[3] = bfhi(w.w); }
; __device__ __forceinline__ void hgC_item(const Bufs& B, int l, int it, unsigned char* shm, const float* hlb, const float* hn) {
;     ...
;     for (int q = 0; q < 2; ++q) {
;         const int idx = tid + 512 * q, t = idx >> 4, k8 = (idx & 15) * 8;
;         f32x4 q0, q1, e0, e1; unpack8(qv[q], q0, q1); unpack8(ev[q], e0, e1);
;         const u32x4 iw = iv[q];
;         const int tx = t ^ (((k8 >> 3) & 7) << 3);
;         const f32x4 c0 = *(const f32x4*)(cumS + t * 128 + k8), c1 = *(const f32x4*)(cumS + t * 128 + k8 + 4), m0v = *(const f32x4*)(cumS + 31 * 128 + k8), m1v = *(const f32x4*)(cumS + 31 * 128 + k8 + 4);
;         const f32x4 l0 = *(const f32x4*)(lbS + k8), l1 = *(const f32x4*)(lbS + k8 + 4);
;         f32x4 x0, x1, y0, y1, z0, z1;
; #pragma unroll
;         for (int j = 0; j < 4; ++j) {
;             x0[j] = q0[j] * __expf(c0[j]); x1[j] = q1[j] * __expf(c1[j]);
;             y0[j] = q0[j] * __expf(fminf(c0[j] - m0v[j], 80.f)); y1[j] = q1[j] * __expf(fminf(c1[j] - m1v[j], 80.f));
;             z0[j] = l0[j] * e0[j] * __expf(fminf(m0v[j] - c0[j], 80.f)); z1[j] = l1[j] * e1[j] * __expf(fminf(m1v[j] - c1[j], 80.f));
;         }
;         *(u32x4*)(qe + t * 136 + k8) = pack8(x0, x1); *(u32x4*)(qa + t * 136 + k8) = pack8(y0, y1); *(u32x4*)(kb + t * 136 + k8) = pack8(z0, z1);
;         iT[(k8 + 0) * 72 + tx] = (bf16_t)(iw.x & 0xffffu); iT[(k8 + 1) * 72 + tx] = (bf16_t)(iw.x >> 16); iT[(k8 + 2) * 72 + tx] = (bf16_t)(iw.y & 0xffffu); iT[(k8 + 3) * 72 + tx] = (bf16_t)(iw.y >> 16);
;         iT[(k8 + 4) * 72 + tx] = (bf16_t)(iw.z & 0xffffu); iT[(k8 + 5) * 72 + tx] = (bf16_t)(iw.z >> 16); iT[(k8 + 6) * 72 + tx] = (bf16_t)(iw.w & 0xffffu); iT[(k8 + 7) * 72 + tx] = (bf16_t)(iw.w >> 16);
;     }
;     __syncthreads();
	v_add_u32_e32 v39, v100, v38
	v_add_u32_e32 v32, s46, v42
	v_mov_b32_e32 v33, s84
	ds_write_b128 v39, v[28:31] offset:33792
	v_cvt_pk_bf16_f32 v28, v96, v97
	v_cvt_pk_bf16_f32 v29, v70, v71
	v_cvt_pk_bf16_f32 v30, v92, v93
	v_cvt_pk_bf16_f32 v31, v74, v75
	v_mad_u32_u24 v33, v65, s76, v33
	v_bitop3_b32 v50, v68, v43, 56 bitop3:0x6c
	ds_write_b128 v39, v[28:31] offset:51200
	v_cvt_pk_bf16_f32 v28, v56, v57
	v_cvt_pk_bf16_f32 v29, v52, v53
	v_cvt_pk_bf16_f32 v30, v34, v35
	v_cvt_pk_bf16_f32 v31, v36, v37
	v_add_u32_e32 v34, v32, v38
	ds_write_b128 v34, v[28:31]
	v_lshl_add_u32 v28, v50, 1, v33
	ds_write_b16 v28, v24
	ds_write_b16_d16_hi v28, v24 offset:144
	ds_write_b16 v28, v25 offset:288
	ds_write_b16_d16_hi v28, v25 offset:432
	ds_write_b16 v28, v26 offset:576
	ds_write_b16_d16_hi v28, v26 offset:720
	ds_write_b16 v28, v27 offset:864
	ds_write_b16_d16_hi v28, v27 offset:1008
	v_lshl_add_u32 v24, v49, 9, v48
	v_lshlrev_b32_e32 v38, 16, v20
	v_and_b32_e32 v39, 0xffff0000, v20
	v_lshlrev_b32_e32 v70, 16, v21
	v_and_b32_e32 v71, 0xffff0000, v21
	v_lshlrev_b32_e32 v72, 16, v22
	v_and_b32_e32 v73, 0xffff0000, v22
	v_lshlrev_b32_e32 v74, 16, v23
	v_and_b32_e32 v75, 0xffff0000, v23
	ds_read_b128 v[20:23], v24
	ds_read_b128 v[24:27], v24 offset:16
	ds_read_b128 v[28:31], v48 offset:15872
	ds_read_b128 v[34:37], v48 offset:15888
	ds_read_b128 v[50:53], v69
	ds_read_b128 v[54:57], v69 offset:16
	s_waitcnt lgkmcnt(5)
	v_mul_f32_e32 v69, 0x3fb8aa3b, v20
	v_exp_f32_e32 v76, v69
	s_waitcnt lgkmcnt(4)
	v_mul_f32_e32 v69, 0x3fb8aa3b, v24
	v_exp_f32_e32 v78, v69
	s_waitcnt lgkmcnt(3)
	v_sub_f32_e32 v69, v20, v28
	v_sub_f32_e32 v20, v28, v20
	v_mul_f32_e32 v28, 0x3fb8aa3b, v21
	v_exp_f32_e32 v77, v28
	v_mul_f32_e32 v28, 0x3fb8aa3b, v25
	v_exp_f32_e32 v79, v28
	v_sub_f32_e32 v28, v21, v29
	v_sub_f32_e32 v21, v29, v21
	v_min_f32_e32 v20, 0x42a00000, v20
	v_min_f32_e32 v28, 0x42a00000, v28
	v_min_f32_e32 v21, 0x42a00000, v21
	v_mul_f32_e32 v20, 0x3fb8aa3b, v20
	v_mul_f32_e32 v28, 0x3fb8aa3b, v28
	v_mul_f32_e32 v21, 0x3fb8aa3b, v21
	v_exp_f32_e32 v20, v20
	v_exp_f32_e32 v81, v28
	s_waitcnt lgkmcnt(2)
	v_sub_f32_e32 v28, v25, v35
	v_exp_f32_e32 v21, v21
	v_min_f32_e32 v28, 0x42a00000, v28
	v_min_f32_e32 v69, 0x42a00000, v69
	v_mul_f32_e32 v28, 0x3fb8aa3b, v28
	v_mul_f32_e32 v69, 0x3fb8aa3b, v69
	v_exp_f32_e32 v83, v28
	s_waitcnt lgkmcnt(1)
	v_pk_mul_f32 v[28:29], v[50:51], v[62:63]
	v_exp_f32_e32 v80, v69
	v_sub_f32_e32 v69, v24, v34
	v_sub_f32_e32 v24, v34, v24
	v_pk_mul_f32 v[28:29], v[28:29], v[20:21]
	v_sub_f32_e32 v20, v35, v25
	v_min_f32_e32 v24, 0x42a00000, v24
	v_min_f32_e32 v20, 0x42a00000, v20
	v_mul_f32_e32 v24, 0x3fb8aa3b, v24
	v_mul_f32_e32 v20, 0x3fb8aa3b, v20
	v_exp_f32_e32 v24, v24
	v_exp_f32_e32 v25, v20
	s_waitcnt lgkmcnt(0)
	v_pk_mul_f32 v[20:21], v[54:55], v[60:61]
	v_min_f32_e32 v69, 0x42a00000, v69
	v_mul_f32_e32 v69, 0x3fb8aa3b, v69
	v_pk_mul_f32 v[24:25], v[20:21], v[24:25]
	v_mul_f32_e32 v21, 0x3fb8aa3b, v26
	v_exp_f32_e32 v34, v21
	v_sub_f32_e32 v21, v22, v30
	v_min_f32_e32 v21, 0x42a00000, v21
	v_mul_f32_e32 v21, 0x3fb8aa3b, v21
	v_exp_f32_e32 v50, v21
	v_sub_f32_e32 v21, v26, v36
	v_min_f32_e32 v21, 0x42a00000, v21
	v_mul_f32_e32 v21, 0x3fb8aa3b, v21
	v_exp_f32_e32 v54, v21
	v_sub_f32_e32 v21, v30, v22
	v_min_f32_e32 v21, 0x42a00000, v21
	v_mul_f32_e32 v21, 0x3fb8aa3b, v21
	v_mul_f32_e32 v20, 0x3fb8aa3b, v22
	v_exp_f32_e32 v22, v21
	v_sub_f32_e32 v21, v36, v26
	v_min_f32_e32 v21, 0x42a00000, v21
	v_mul_f32_e32 v21, 0x3fb8aa3b, v21
	v_exp_f32_e32 v26, v21
	v_mul_f32_e32 v21, 0x3fb8aa3b, v23
	v_exp_f32_e32 v20, v20
	v_exp_f32_e32 v21, v21
	v_mul_f32_e32 v30, 0x3fb8aa3b, v27
	v_exp_f32_e32 v35, v30
	v_sub_f32_e32 v30, v23, v31
	v_pk_mul_f32 v[60:61], v[20:21], v[70:71]
	v_sub_f32_e32 v20, v27, v37
	v_min_f32_e32 v20, 0x42a00000, v20
	v_mul_f32_e32 v20, 0x3fb8aa3b, v20
	v_exp_f32_e32 v55, v20
	v_sub_f32_e32 v20, v31, v23
	v_min_f32_e32 v20, 0x42a00000, v20
	v_mul_f32_e32 v20, 0x3fb8aa3b, v20
	v_exp_f32_e32 v23, v20
	v_min_f32_e32 v30, 0x42a00000, v30
	v_mul_f32_e32 v30, 0x3fb8aa3b, v30
	v_pk_mul_f32 v[20:21], v[52:53], v[58:59]
	v_exp_f32_e32 v51, v30
	v_pk_mul_f32 v[30:31], v[20:21], v[22:23]
	v_sub_f32_e32 v20, v37, v27
	v_min_f32_e32 v20, 0x42a00000, v20
	v_exp_f32_e32 v82, v69
	v_mul_f32_e32 v20, 0x3fb8aa3b, v20
	v_exp_f32_e32 v27, v20
	v_pk_mul_f32 v[34:35], v[34:35], v[74:75]
	v_pk_mul_f32 v[80:81], v[80:81], v[38:39]
	v_pk_mul_f32 v[38:39], v[76:77], v[38:39]
	v_pk_mul_f32 v[76:77], v[82:83], v[72:73]
	v_pk_mul_f32 v[72:73], v[78:79], v[72:73]
	v_pk_mul_f32 v[20:21], v[56:57], v[40:41]
	v_cvt_pk_bf16_f32 v23, v34, v35
	v_mul_lo_u32 v34, v49, s77
	v_pk_mul_f32 v[50:51], v[50:51], v[70:71]
	v_pk_mul_f32 v[54:55], v[54:55], v[74:75]
	v_pk_mul_f32 v[26:27], v[20:21], v[26:27]
	v_cvt_pk_bf16_f32 v20, v38, v39
	v_cvt_pk_bf16_f32 v21, v60, v61
	v_cvt_pk_bf16_f32 v22, v72, v73
	v_add_u32_e32 v35, v100, v34
	ds_write_b128 v35, v[20:23] offset:33792
	v_cvt_pk_bf16_f32 v20, v80, v81
	v_cvt_pk_bf16_f32 v21, v50, v51
	v_cvt_pk_bf16_f32 v22, v76, v77
	v_cvt_pk_bf16_f32 v23, v54, v55
	v_bitop3_b32 v36, v49, v68, 56 bitop3:0x78
	ds_write_b128 v35, v[20:23] offset:51200
	v_cvt_pk_bf16_f32 v20, v28, v29
	v_cvt_pk_bf16_f32 v21, v30, v31
	v_cvt_pk_bf16_f32 v22, v24, v25
	v_cvt_pk_bf16_f32 v23, v26, v27
	v_add_u32_e32 v24, v32, v34
	ds_write_b128 v24, v[20:23]
	v_lshl_add_u32 v20, v36, 1, v33
	s_waitcnt vmcnt(0)
	ds_write_b16 v20, v16
	ds_write_b16_d16_hi v20, v16 offset:144
	ds_write_b16 v20, v17 offset:288
	ds_write_b16_d16_hi v20, v17 offset:432
	ds_write_b16 v20, v18 offset:576
	ds_write_b16_d16_hi v20, v18 offset:720
	ds_write_b16 v20, v19 offset:864
	ds_write_b16_d16_hi v20, v19 offset:1008
	v_lshrrev_b32_e32 v16, 2, v67
	v_and_b32_e32 v21, 15, v67
	v_and_b32_e32 v23, 12, v16
	s_waitcnt lgkmcnt(0)
	s_barrier
; __device__ __forceinline__ bf16_t f2bf(float f) { unsigned u = __float_as_uint(f); u += 0x7FFFu + ((u >> 16) & 1u); return (bf16_t)(u >> 16); }
; __device__ __forceinline__ void hgC_item(const Bufs& B, int l, int it, unsigned char* shm, const float* hlb, const float* hn) {
;     ...
;     for (int tile = wid; tile < 16; tile += 8) {
;         const int tm = tile >> 2, tn = tile & 3;
;         f32x4 acc = {0.f, 0.f, 0.f, 0.f};
;         if (tn <= tm) acc = mma_tile(qa + tm * 16 * 136, 136, kb + tn * 16 * 136, 136, 128, lane);
;         const int sc = tn * 16 + (lane & 15);
; #pragma unroll
;         for (int j = 0; j < 4; ++j) { const int t = tm * 16 + (lane >> 4) * 4 + j; P[t * 72 + sc] = f2bf(sc <= t ? acc[j] : 0.f); }
;     }
	s_mov_b64 s[2:3], exec
	v_readfirstlane_b32 s34, v66
	v_mad_u32_u24 v20, v21, s77, v176
	v_and_b32_e32 v24, 3, v66
	v_mul_u32_u24_e32 v17, 0x1100, v24
	v_lshl_or_b32 v25, v24, 4, v21
	v_add3_u32 v26, s46, v20, v17
	v_lshl_add_u32 v22, v25, 1, s47
	s_lshr_b32 s34, s34, 2
	s_mul_i32 s35, s34, 0x1100
	s_lshl_b32 s34, s34, 4
	ds_read_b128 v[80:83], v26
	ds_read_b128 v[84:87], v26 offset:64
	ds_read_b128 v[88:91], v26 offset:128
	ds_read_b128 v[92:95], v26 offset:192
	v_add_u32_e32 v27, s35, v20
	ds_read_b128 v[96:99], v27 offset:51200
	ds_read_b128 v[100:103], v27 offset:51264
	ds_read_b128 v[104:107], v27 offset:51328
	ds_read_b128 v[108:111], v27 offset:51392
	ds_read_b128 v[112:115], v27 offset:59904
	ds_read_b128 v[116:119], v27 offset:59968
	ds_read_b128 v[120:123], v27 offset:60032
	ds_read_b128 v[124:127], v27 offset:60096
	v_add_u32_e32 v72, s34, v23
	v_mad_u32_u24 v75, v72, s76, v22
	s_waitcnt lgkmcnt(3)
	v_mfma_f32_16x16x32_bf16 v[60:63], v[96:99], v[80:83], 0
	v_mfma_f32_16x16x32_bf16 v[68:71], v[112:115], v[80:83], 0
	s_waitcnt lgkmcnt(2)
	v_mfma_f32_16x16x32_bf16 v[60:63], v[100:103], v[84:87], v[60:63]
	v_mfma_f32_16x16x32_bf16 v[68:71], v[116:119], v[84:87], v[68:71]
	s_waitcnt lgkmcnt(1)
	v_mfma_f32_16x16x32_bf16 v[60:63], v[104:107], v[88:91], v[60:63]
	v_mfma_f32_16x16x32_bf16 v[68:71], v[120:123], v[88:91], v[68:71]
	s_waitcnt lgkmcnt(0)
	v_mfma_f32_16x16x32_bf16 v[60:63], v[108:111], v[92:95], v[60:63]
	v_mfma_f32_16x16x32_bf16 v[68:71], v[124:127], v[92:95], v[68:71]
	s_nop 7
	s_nop 3
	v_add_u32_e32 v73, 1, v72
	v_add_u32_e32 v74, 2, v72
	v_add_u32_e32 v76, 3, v72
	v_cmp_le_i32_e64 s[36:37], v25, v72
	v_cmp_le_i32_e64 s[38:39], v25, v73
	v_cmp_le_i32_e64 s[40:41], v25, v74
	v_cmp_le_i32_e64 vcc, v25, v76
	v_cndmask_b32_e64 v60, 0, v60, s[36:37]
	v_cndmask_b32_e64 v61, 0, v61, s[38:39]
	v_cndmask_b32_e64 v62, 0, v62, s[40:41]
	v_cndmask_b32_e64 v63, 0, v63, vcc
	v_bfe_u32 v77, v60, 16, 1
	v_bfe_u32 v73, v61, 16, 1
	v_bfe_u32 v74, v62, 16, 1
	v_bfe_u32 v76, v63, 16, 1
	v_add3_u32 v60, v60, v77, s78
	ds_write_b16_d16_hi v75, v60
	v_add3_u32 v61, v61, v73, s78
	ds_write_b16_d16_hi v75, v61 offset:144
	v_add3_u32 v62, v62, v74, s78
	ds_write_b16_d16_hi v75, v62 offset:288
	v_add3_u32 v63, v63, v76, s78
	ds_write_b16_d16_hi v75, v63 offset:432
	v_add_u32_e32 v72, 32, v72
	v_add_u32_e32 v73, 1, v72
	v_add_u32_e32 v74, 2, v72
	v_add_u32_e32 v76, 3, v72
	v_cmp_le_i32_e64 s[36:37], v25, v72
	v_cmp_le_i32_e64 s[38:39], v25, v73
	v_cmp_le_i32_e64 s[40:41], v25, v74
	v_cmp_le_i32_e64 vcc, v25, v76
	v_cndmask_b32_e64 v68, 0, v68, s[36:37]
	v_cndmask_b32_e64 v69, 0, v69, s[38:39]
	v_cndmask_b32_e64 v70, 0, v70, s[40:41]
	v_cndmask_b32_e64 v71, 0, v71, vcc
	v_bfe_u32 v77, v68, 16, 1
	v_bfe_u32 v73, v69, 16, 1
	v_bfe_u32 v74, v70, 16, 1
	v_bfe_u32 v76, v71, 16, 1
	v_add3_u32 v68, v68, v77, s78
	ds_write_b16_d16_hi v75, v68 offset:4608
	v_add3_u32 v69, v69, v73, s78
	ds_write_b16_d16_hi v75, v69 offset:4752
	v_add3_u32 v70, v70, v74, s78
	ds_write_b16_d16_hi v75, v70 offset:4896
	v_add3_u32 v71, v71, v76, s78
	ds_write_b16_d16_hi v75, v71 offset:5040
